# attention softmax cross-group max / sum: the two cross-row levels exchange through v_permlane16_swap / v_permlane32_swap on a copy instead of ds_bpermute round trips
# speedup vs baseline: 1.0137x; 1.0054x over previous
; #define LAS __attribute__((address_space(3)))
; #define LDS_WAIT() asm volatile("s_waitcnt lgkmcnt(0)" ::: "memory")
; __device__ __forceinline__ void kv8_pv(const u32x4 (&buf)[8], f32x2v (&o2)[8], const LAS float* srow, int b) {
;     const LAS f32x4* p4 = (const LAS f32x4*)(srow + b * 8);
;     const f32x4 p0 = p4[0], p1 = p4[1];
;     const float p[8] = {p0.x, p0.y, p0.z, p0.w, p1.x, p1.y, p1.z, p1.w};
; #pragma unroll
;     for (int u = 0; u < 8; ++u) {
;         const u32x4 v = buf[u]; const f32x2v pp = {p[u], p[u]};
;         o2[0] = __builtin_elementwise_fma(pp, __builtin_amdgcn_cvt_pk_f32_fp8(v.x, false), o2[0]); o2[1] = __builtin_elementwise_fma(pp, __builtin_amdgcn_cvt_pk_f32_fp8(v.x, true), o2[1]);
;         o2[2] = __builtin_elementwise_fma(pp, __builtin_amdgcn_cvt_pk_f32_fp8(v.y, false), o2[2]); o2[3] = __builtin_elementwise_fma(pp, __builtin_amdgcn_cvt_pk_f32_fp8(v.y, true), o2[3]);
;         o2[4] = __builtin_elementwise_fma(pp, __builtin_amdgcn_cvt_pk_f32_fp8(v.z, false), o2[4]); o2[5] = __builtin_elementwise_fma(pp, __builtin_amdgcn_cvt_pk_f32_fp8(v.z, true), o2[5]);
;         o2[6] = __builtin_elementwise_fma(pp, __builtin_amdgcn_cvt_pk_f32_fp8(v.w, false), o2[6]); o2[7] = __builtin_elementwise_fma(pp, __builtin_amdgcn_cvt_pk_f32_fp8(v.w, true), o2[7]);
;     }
; __device__ __forceinline__ void attn_query8(const unsigned char* __restrict__ KV8, const bf16_t* __restrict__ Z, const int* __restrict__ SEL, bf16_t* __restrict__ YMIX, int t, LAS float* sbuf  ) {
;     ...
;     for (int h = 0; h < 8; ++h) {
;         float sv[4]; float mx = -__builtin_inff();
; #pragma unroll
;         for (int jj = 0; jj < 4; ++jj) { const int j = lane + 64 * jj; const float s = sbuf[h * 256 + j]; sv[jj] = (j < nsel) ? s : -__builtin_inff(); mx = fmaxf(mx, sv[jj]); }
;         mx = wave_max(mx); float sm = 0.f;
; #pragma unroll
;         for (int jj = 0; jj < 4; ++jj) { const int j = lane + 64 * jj; sv[jj] = (j < nsel) ? __expf(sv[jj] - mx) : 0.f; sm += sv[jj]; }
;         sm = wave_sum(sm); const float inv = 1.f / sm;
; #pragma unroll
;         for (int jj = 0; jj < 4; ++jj) sbuf[h * 256 + lane + 64 * jj] = sv[jj] * inv;
;     }
;     LDS_WAIT();
.Latt_nomask:
	v_max3_f32 v134, v150, v151, v152
	v_max3_f32 v134, v134, v153, v154
	v_max3_f32 v134, v134, v155, v156
	v_max3_f32 v134, v134, v157, v158
	v_max3_f32 v134, v134, v159, v160
	v_max3_f32 v134, v134, v161, v162
	v_max3_f32 v134, v134, v163, v164
	v_max3_f32 v134, v134, v165, v166
	v_max3_f32 v134, v134, v167, v168
	v_max3_f32 v134, v134, v169, v170
	v_max3_f32 v134, v134, v171, v172
	v_max3_f32 v134, v134, v173, v174
	v_max3_f32 v134, v134, v175, v176
	v_max3_f32 v134, v134, v177, v178
	v_max3_f32 v134, v134, v179, v180
	v_max_f32_e32 v134, v134, v181
	s_nop 1
	v_mov_b32_dpp v135, v134 row_ror:8 row_mask:0xf bank_mask:0xf
	s_nop 0
	v_max_f32_e32 v134, v134, v135
	v_mov_b32_e32 v135, v134
	s_nop 1
	v_permlane16_swap_b32_e32 v134, v135
	v_max_f32_e32 v134, v134, v135
	v_mov_b32_e32 v135, v134
	s_nop 1
	v_permlane32_swap_b32_e32 v134, v135
	v_max_f32_e32 v134, v134, v135
	v_mul_f32_e32 v134, 0xbfb8aa3b, v134
	v_fma_f32 v150, v150, s28, v134
	v_fma_f32 v151, v151, s28, v134
	v_fma_f32 v152, v152, s28, v134
	v_fma_f32 v153, v153, s28, v134
	v_fma_f32 v154, v154, s28, v134
	v_fma_f32 v155, v155, s28, v134
	v_fma_f32 v156, v156, s28, v134
	v_fma_f32 v157, v157, s28, v134
	v_fma_f32 v158, v158, s28, v134
	v_fma_f32 v159, v159, s28, v134
	v_fma_f32 v160, v160, s28, v134
	v_fma_f32 v161, v161, s28, v134
	v_fma_f32 v162, v162, s28, v134
	v_fma_f32 v163, v163, s28, v134
	v_fma_f32 v164, v164, s28, v134
	v_fma_f32 v165, v165, s28, v134
	v_fma_f32 v166, v166, s28, v134
	v_fma_f32 v167, v167, s28, v134
	v_fma_f32 v168, v168, s28, v134
	v_fma_f32 v169, v169, s28, v134
	v_fma_f32 v170, v170, s28, v134
	v_fma_f32 v171, v171, s28, v134
	v_fma_f32 v172, v172, s28, v134
	v_fma_f32 v173, v173, s28, v134
	v_fma_f32 v174, v174, s28, v134
	v_fma_f32 v175, v175, s28, v134
	v_fma_f32 v176, v176, s28, v134
	v_fma_f32 v177, v177, s28, v134
	v_fma_f32 v178, v178, s28, v134
	v_fma_f32 v179, v179, s28, v134
	v_fma_f32 v180, v180, s28, v134
	v_fma_f32 v181, v181, s28, v134
	v_exp_f32_e32 v150, v150
	v_exp_f32_e32 v151, v151
	v_exp_f32_e32 v152, v152
	v_exp_f32_e32 v153, v153
	v_exp_f32_e32 v154, v154
	v_exp_f32_e32 v155, v155
	v_exp_f32_e32 v156, v156
	v_exp_f32_e32 v157, v157
	v_exp_f32_e32 v158, v158
	v_exp_f32_e32 v159, v159
	v_exp_f32_e32 v160, v160
	v_exp_f32_e32 v161, v161
	v_exp_f32_e32 v162, v162
	v_exp_f32_e32 v163, v163
	v_exp_f32_e32 v164, v164
	v_exp_f32_e32 v165, v165
	v_exp_f32_e32 v166, v166
	v_exp_f32_e32 v167, v167
	v_exp_f32_e32 v168, v168
	v_exp_f32_e32 v169, v169
	v_exp_f32_e32 v170, v170
	v_exp_f32_e32 v171, v171
	v_exp_f32_e32 v172, v172
	v_exp_f32_e32 v173, v173
	v_exp_f32_e32 v174, v174
	v_exp_f32_e32 v175, v175
	v_exp_f32_e32 v176, v176
	v_exp_f32_e32 v177, v177
	v_exp_f32_e32 v178, v178
	v_exp_f32_e32 v179, v179
	v_exp_f32_e32 v180, v180
	v_exp_f32_e32 v181, v181
	s_nop 0
	v_add_f32_e32 v134, v150, v151
	v_add_f32_e32 v134, v134, v152
	v_add_f32_e32 v134, v134, v153
	v_add_f32_e32 v134, v134, v154
	v_add_f32_e32 v134, v134, v155
	v_add_f32_e32 v134, v134, v156
	v_add_f32_e32 v134, v134, v157
	v_add_f32_e32 v134, v134, v158
	v_add_f32_e32 v134, v134, v159
	v_add_f32_e32 v134, v134, v160
	v_add_f32_e32 v134, v134, v161
	v_add_f32_e32 v134, v134, v162
	v_add_f32_e32 v134, v134, v163
	v_add_f32_e32 v134, v134, v164
	v_add_f32_e32 v134, v134, v165
	v_add_f32_e32 v134, v134, v166
	v_add_f32_e32 v134, v134, v167
	v_add_f32_e32 v134, v134, v168
	v_add_f32_e32 v134, v134, v169
	v_add_f32_e32 v134, v134, v170
	v_add_f32_e32 v134, v134, v171
	v_add_f32_e32 v134, v134, v172
	v_add_f32_e32 v134, v134, v173
	v_add_f32_e32 v134, v134, v174
	v_add_f32_e32 v134, v134, v175
	v_add_f32_e32 v134, v134, v176
	v_add_f32_e32 v134, v134, v177
	v_add_f32_e32 v134, v134, v178
	v_add_f32_e32 v134, v134, v179
	v_add_f32_e32 v134, v134, v180
	v_add_f32_e32 v134, v134, v181
	s_nop 1
	v_mov_b32_dpp v135, v134 row_ror:8 row_mask:0xf bank_mask:0xf
	s_nop 0
	v_add_f32_e32 v134, v134, v135
	v_mov_b32_e32 v135, v134
	s_nop 1
	v_permlane16_swap_b32_e32 v134, v135
	v_add_f32_e32 v134, v134, v135
	v_mov_b32_e32 v135, v134
	s_nop 1
	v_permlane32_swap_b32_e32 v134, v135
	v_add_f32_e32 v134, v134, v135
	v_div_scale_f32 v132, s[8:9], v134, v134, 1.0
	v_rcp_f32_e32 v135, v132
	v_div_scale_f32 v133, vcc, 1.0, v134, 1.0
	v_fma_f32 v136, -v132, v135, 1.0
	v_fmac_f32_e32 v135, v136, v135
	v_mul_f32_e32 v136, v133, v135
	v_fma_f32 v137, -v132, v136, v133
	v_fmac_f32_e32 v136, v137, v135
	v_fma_f32 v132, -v132, v136, v133
	s_nop 1
	v_div_fmas_f32 v132, v132, v135, v136
	v_div_fixup_f32 v134, v132, v134, 1.0
	v_mov_b32_e32 v149, v134
	s_waitcnt vmcnt(31)
	ds_write_b32 v148, v240 offset:0
	ds_write_b32 v148, v241 offset:32
	ds_write_b32 v148, v242 offset:64
	ds_write_b32 v148, v243 offset:96
	v_cvt_pk_f32_fp8_e32 v[214:215], v0
	v_cvt_pk_f32_fp8_sdwa v[216:217], v0 src0_sel:WORD_1
	v_pk_mul_f32 v[198:199], v[150:151], v[214:215] op_sel_hi:[0,1]
	v_pk_mul_f32 v[200:201], v[150:151], v[216:217] op_sel_hi:[0,1]
	v_cvt_pk_f32_fp8_e32 v[218:219], v1
	v_cvt_pk_f32_fp8_sdwa v[220:221], v1 src0_sel:WORD_1
	v_pk_mul_f32 v[202:203], v[150:151], v[218:219] op_sel_hi:[0,1]
	v_pk_mul_f32 v[204:205], v[150:151], v[220:221] op_sel_hi:[0,1]
	v_cvt_pk_f32_fp8_e32 v[214:215], v2
	v_cvt_pk_f32_fp8_sdwa v[216:217], v2 src0_sel:WORD_1
	v_pk_mul_f32 v[206:207], v[150:151], v[214:215] op_sel_hi:[0,1]
	v_pk_mul_f32 v[208:209], v[150:151], v[216:217] op_sel_hi:[0,1]
	v_cvt_pk_f32_fp8_e32 v[218:219], v3
	v_cvt_pk_f32_fp8_sdwa v[220:221], v3 src0_sel:WORD_1
	v_pk_mul_f32 v[210:211], v[150:151], v[218:219] op_sel_hi:[0,1]
	v_pk_mul_f32 v[212:213], v[150:151], v[220:221] op_sel_hi:[0,1]
	s_waitcnt vmcnt(30)
; #define LAS __attribute__((address_space(3)))
; __device__ __forceinline__ void kv8_issue(u32x4 (&buf)[8], __amdgpu_buffer_rsrc_t rs, int voff  , int sbase  , const int (&iv)[4], int b) {
;     const int jj = b >> 3, l0 = (b & 7) * 8;
;     const int ivb = (jj == 0) ? iv[0] : (jj == 1) ? iv[1] : (jj == 2) ? iv[2] : iv[3];
; #pragma unroll
;     for (int u = 0; u < 8; ++u) { const int si = __builtin_amdgcn_readlane(ivb, l0 + u); buf[u] = __builtin_amdgcn_raw_buffer_load_b128(rs, voff, si * 2048 + sbase, KV8_AUX); }
; }
; __device__ __forceinline__ void kv8_pv(const u32x4 (&buf)[8], f32x2v (&o2)[8], const LAS float* srow, int b) {
;     const LAS f32x4* p4 = (const LAS f32x4*)(srow + b * 8);
;     const f32x4 p0 = p4[0], p1 = p4[1];
;     const float p[8] = {p0.x, p0.y, p0.z, p0.w, p1.x, p1.y, p1.z, p1.w};
; #pragma unroll
;     for (int u = 0; u < 8; ++u) {
;         const u32x4 v = buf[u]; const f32x2v pp = {p[u], p[u]};
;         o2[0] = __builtin_elementwise_fma(pp, __builtin_amdgcn_cvt_pk_f32_fp8(v.x, false), o2[0]); o2[1] = __builtin_elementwise_fma(pp, __builtin_amdgcn_cvt_pk_f32_fp8(v.x, true), o2[1]);
;         o2[2] = __builtin_elementwise_fma(pp, __builtin_amdgcn_cvt_pk_f32_fp8(v.y, false), o2[2]); o2[3] = __builtin_elementwise_fma(pp, __builtin_amdgcn_cvt_pk_f32_fp8(v.y, true), o2[3]);
;         o2[4] = __builtin_elementwise_fma(pp, __builtin_amdgcn_cvt_pk_f32_fp8(v.z, false), o2[4]); o2[5] = __builtin_elementwise_fma(pp, __builtin_amdgcn_cvt_pk_f32_fp8(v.z, true), o2[5]);
;         o2[6] = __builtin_elementwise_fma(pp, __builtin_amdgcn_cvt_pk_f32_fp8(v.w, false), o2[6]); o2[7] = __builtin_elementwise_fma(pp, __builtin_amdgcn_cvt_pk_f32_fp8(v.w, true), o2[7]);
;     }
	v_cvt_pk_f32_fp8_e32 v[214:215], v4
	v_cvt_pk_f32_fp8_sdwa v[216:217], v4 src0_sel:WORD_1
	v_pk_fma_f32 v[198:199], v[150:151], v[214:215], v[198:199] op_sel:[1,0,0]
	v_pk_fma_f32 v[200:201], v[150:151], v[216:217], v[200:201] op_sel:[1,0,0]
	v_cvt_pk_f32_fp8_e32 v[218:219], v5
	v_cvt_pk_f32_fp8_sdwa v[220:221], v5 src0_sel:WORD_1
	v_pk_fma_f32 v[202:203], v[150:151], v[218:219], v[202:203] op_sel:[1,0,0]
	v_pk_fma_f32 v[204:205], v[150:151], v[220:221], v[204:205] op_sel:[1,0,0]
	v_cvt_pk_f32_fp8_e32 v[214:215], v6
	v_cvt_pk_f32_fp8_sdwa v[216:217], v6 src0_sel:WORD_1
	v_pk_fma_f32 v[206:207], v[150:151], v[214:215], v[206:207] op_sel:[1,0,0]
	v_pk_fma_f32 v[208:209], v[150:151], v[216:217], v[208:209] op_sel:[1,0,0]
	v_cvt_pk_f32_fp8_e32 v[218:219], v7
	v_cvt_pk_f32_fp8_sdwa v[220:221], v7 src0_sel:WORD_1
	v_pk_fma_f32 v[210:211], v[150:151], v[218:219], v[210:211] op_sel:[1,0,0]
	v_pk_fma_f32 v[212:213], v[150:151], v[220:221], v[212:213] op_sel:[1,0,0]
	s_waitcnt vmcnt(29)
	v_cvt_pk_f32_fp8_e32 v[214:215], v8
	v_cvt_pk_f32_fp8_sdwa v[216:217], v8 src0_sel:WORD_1
	v_pk_fma_f32 v[198:199], v[152:153], v[214:215], v[198:199] op_sel_hi:[0,1,1]
	v_pk_fma_f32 v[200:201], v[152:153], v[216:217], v[200:201] op_sel_hi:[0,1,1]
	v_cvt_pk_f32_fp8_e32 v[218:219], v9
	v_cvt_pk_f32_fp8_sdwa v[220:221], v9 src0_sel:WORD_1
	v_pk_fma_f32 v[202:203], v[152:153], v[218:219], v[202:203] op_sel_hi:[0,1,1]
	v_pk_fma_f32 v[204:205], v[152:153], v[220:221], v[204:205] op_sel_hi:[0,1,1]
	v_cvt_pk_f32_fp8_e32 v[214:215], v10
	v_cvt_pk_f32_fp8_sdwa v[216:217], v10 src0_sel:WORD_1
	v_pk_fma_f32 v[206:207], v[152:153], v[214:215], v[206:207] op_sel_hi:[0,1,1]
	v_pk_fma_f32 v[208:209], v[152:153], v[216:217], v[208:209] op_sel_hi:[0,1,1]
	v_cvt_pk_f32_fp8_e32 v[218:219], v11
	v_cvt_pk_f32_fp8_sdwa v[220:221], v11 src0_sel:WORD_1
	v_pk_fma_f32 v[210:211], v[152:153], v[218:219], v[210:211] op_sel_hi:[0,1,1]
	v_pk_fma_f32 v[212:213], v[152:153], v[220:221], v[212:213] op_sel_hi:[0,1,1]
	s_waitcnt vmcnt(28)
	v_cvt_pk_f32_fp8_e32 v[214:215], v12
	v_cvt_pk_f32_fp8_sdwa v[216:217], v12 src0_sel:WORD_1
	v_pk_fma_f32 v[198:199], v[152:153], v[214:215], v[198:199] op_sel:[1,0,0]
	v_pk_fma_f32 v[200:201], v[152:153], v[216:217], v[200:201] op_sel:[1,0,0]
	v_cvt_pk_f32_fp8_e32 v[218:219], v13
	v_cvt_pk_f32_fp8_sdwa v[220:221], v13 src0_sel:WORD_1
	v_pk_fma_f32 v[202:203], v[152:153], v[218:219], v[202:203] op_sel:[1,0,0]
	v_pk_fma_f32 v[204:205], v[152:153], v[220:221], v[204:205] op_sel:[1,0,0]
	v_cvt_pk_f32_fp8_e32 v[214:215], v14
	v_cvt_pk_f32_fp8_sdwa v[216:217], v14 src0_sel:WORD_1
	v_pk_fma_f32 v[206:207], v[152:153], v[214:215], v[206:207] op_sel:[1,0,0]
	v_pk_fma_f32 v[208:209], v[152:153], v[216:217], v[208:209] op_sel:[1,0,0]
	v_cvt_pk_f32_fp8_e32 v[218:219], v15
	v_cvt_pk_f32_fp8_sdwa v[220:221], v15 src0_sel:WORD_1
	v_pk_fma_f32 v[210:211], v[152:153], v[218:219], v[210:211] op_sel:[1,0,0]
	v_pk_fma_f32 v[212:213], v[152:153], v[220:221], v[212:213] op_sel:[1,0,0]
	ds_read_b128 v[150:153], v139 offset:0
	s_waitcnt vmcnt(27)
	v_cvt_pk_f32_fp8_e32 v[214:215], v16
	v_cvt_pk_f32_fp8_sdwa v[216:217], v16 src0_sel:WORD_1
	v_pk_fma_f32 v[198:199], v[154:155], v[214:215], v[198:199] op_sel_hi:[0,1,1]
	v_pk_fma_f32 v[200:201], v[154:155], v[216:217], v[200:201] op_sel_hi:[0,1,1]
	v_cvt_pk_f32_fp8_e32 v[218:219], v17
	v_cvt_pk_f32_fp8_sdwa v[220:221], v17 src0_sel:WORD_1
	v_pk_fma_f32 v[202:203], v[154:155], v[218:219], v[202:203] op_sel_hi:[0,1,1]
	v_pk_fma_f32 v[204:205], v[154:155], v[220:221], v[204:205] op_sel_hi:[0,1,1]
	v_cvt_pk_f32_fp8_e32 v[214:215], v18
	v_cvt_pk_f32_fp8_sdwa v[216:217], v18 src0_sel:WORD_1
	v_pk_fma_f32 v[206:207], v[154:155], v[214:215], v[206:207] op_sel_hi:[0,1,1]
	v_pk_fma_f32 v[208:209], v[154:155], v[216:217], v[208:209] op_sel_hi:[0,1,1]
	v_cvt_pk_f32_fp8_e32 v[218:219], v19
	v_cvt_pk_f32_fp8_sdwa v[220:221], v19 src0_sel:WORD_1
	v_pk_fma_f32 v[210:211], v[154:155], v[218:219], v[210:211] op_sel_hi:[0,1,1]
	v_pk_fma_f32 v[212:213], v[154:155], v[220:221], v[212:213] op_sel_hi:[0,1,1]
	s_waitcnt vmcnt(26)
	v_cvt_pk_f32_fp8_e32 v[214:215], v20
	v_cvt_pk_f32_fp8_sdwa v[216:217], v20 src0_sel:WORD_1
	v_pk_fma_f32 v[198:199], v[154:155], v[214:215], v[198:199] op_sel:[1,0,0]
	v_pk_fma_f32 v[200:201], v[154:155], v[216:217], v[200:201] op_sel:[1,0,0]
	v_cvt_pk_f32_fp8_e32 v[218:219], v21
	v_cvt_pk_f32_fp8_sdwa v[220:221], v21 src0_sel:WORD_1
	v_pk_fma_f32 v[202:203], v[154:155], v[218:219], v[202:203] op_sel:[1,0,0]
	v_pk_fma_f32 v[204:205], v[154:155], v[220:221], v[204:205] op_sel:[1,0,0]
	v_cvt_pk_f32_fp8_e32 v[214:215], v22
	v_cvt_pk_f32_fp8_sdwa v[216:217], v22 src0_sel:WORD_1
	v_pk_fma_f32 v[206:207], v[154:155], v[214:215], v[206:207] op_sel:[1,0,0]
	v_pk_fma_f32 v[208:209], v[154:155], v[216:217], v[208:209] op_sel:[1,0,0]
	v_cvt_pk_f32_fp8_e32 v[218:219], v23
	v_cvt_pk_f32_fp8_sdwa v[220:221], v23 src0_sel:WORD_1
	v_pk_fma_f32 v[210:211], v[154:155], v[218:219], v[210:211] op_sel:[1,0,0]
	v_pk_fma_f32 v[212:213], v[154:155], v[220:221], v[212:213] op_sel:[1,0,0]
	s_waitcnt lgkmcnt(0)
	v_lshl_add_u32 v150, v150, 8, v138
	v_lshl_add_u32 v151, v151, 8, v138
	v_lshl_add_u32 v152, v152, 8, v138
	v_lshl_add_u32 v153, v153, 8, v138
	buffer_load_dwordx4 v[0:3], v150, s[16:19], s26 offen
	buffer_load_dwordx4 v[4:7], v151, s[16:19], s26 offen
	buffer_load_dwordx4 v[8:11], v152, s[16:19], s26 offen
	buffer_load_dwordx4 v[12:15], v153, s[16:19], s26 offen
	s_waitcnt vmcnt(29)
; #define LAS __attribute__((address_space(3)))
; __device__ __forceinline__ void kv8_issue(u32x4 (&buf)[8], __amdgpu_buffer_rsrc_t rs, int voff  , int sbase  , const int (&iv)[4], int b) {
;     const int jj = b >> 3, l0 = (b & 7) * 8;
;     const int ivb = (jj == 0) ? iv[0] : (jj == 1) ? iv[1] : (jj == 2) ? iv[2] : iv[3];
; #pragma unroll
;     for (int u = 0; u < 8; ++u) { const int si = __builtin_amdgcn_readlane(ivb, l0 + u); buf[u] = __builtin_amdgcn_raw_buffer_load_b128(rs, voff, si * 2048 + sbase, KV8_AUX); }
; }
; __device__ __forceinline__ void kv8_pv(const u32x4 (&buf)[8], f32x2v (&o2)[8], const LAS float* srow, int b) {
;     const LAS f32x4* p4 = (const LAS f32x4*)(srow + b * 8);
;     const f32x4 p0 = p4[0], p1 = p4[1];
;     const float p[8] = {p0.x, p0.y, p0.z, p0.w, p1.x, p1.y, p1.z, p1.w};
; #pragma unroll
;     for (int u = 0; u < 8; ++u) {
;         const u32x4 v = buf[u]; const f32x2v pp = {p[u], p[u]};
;         o2[0] = __builtin_elementwise_fma(pp, __builtin_amdgcn_cvt_pk_f32_fp8(v.x, false), o2[0]); o2[1] = __builtin_elementwise_fma(pp, __builtin_amdgcn_cvt_pk_f32_fp8(v.x, true), o2[1]);
;         o2[2] = __builtin_elementwise_fma(pp, __builtin_amdgcn_cvt_pk_f32_fp8(v.y, false), o2[2]); o2[3] = __builtin_elementwise_fma(pp, __builtin_amdgcn_cvt_pk_f32_fp8(v.y, true), o2[3]);
;         o2[4] = __builtin_elementwise_fma(pp, __builtin_amdgcn_cvt_pk_f32_fp8(v.z, false), o2[4]); o2[5] = __builtin_elementwise_fma(pp, __builtin_amdgcn_cvt_pk_f32_fp8(v.z, true), o2[5]);
;         o2[6] = __builtin_elementwise_fma(pp, __builtin_amdgcn_cvt_pk_f32_fp8(v.w, false), o2[6]); o2[7] = __builtin_elementwise_fma(pp, __builtin_amdgcn_cvt_pk_f32_fp8(v.w, true), o2[7]);
;     }
	v_cvt_pk_f32_fp8_e32 v[214:215], v24
	v_cvt_pk_f32_fp8_sdwa v[216:217], v24 src0_sel:WORD_1
	v_pk_fma_f32 v[198:199], v[156:157], v[214:215], v[198:199] op_sel_hi:[0,1,1]
	v_pk_fma_f32 v[200:201], v[156:157], v[216:217], v[200:201] op_sel_hi:[0,1,1]
	v_cvt_pk_f32_fp8_e32 v[218:219], v25
	v_cvt_pk_f32_fp8_sdwa v[220:221], v25 src0_sel:WORD_1
	v_pk_fma_f32 v[202:203], v[156:157], v[218:219], v[202:203] op_sel_hi:[0,1,1]
	v_pk_fma_f32 v[204:205], v[156:157], v[220:221], v[204:205] op_sel_hi:[0,1,1]
	v_cvt_pk_f32_fp8_e32 v[214:215], v26
	v_cvt_pk_f32_fp8_sdwa v[216:217], v26 src0_sel:WORD_1
	v_pk_fma_f32 v[206:207], v[156:157], v[214:215], v[206:207] op_sel_hi:[0,1,1]
	v_pk_fma_f32 v[208:209], v[156:157], v[216:217], v[208:209] op_sel_hi:[0,1,1]
	v_cvt_pk_f32_fp8_e32 v[218:219], v27
	v_cvt_pk_f32_fp8_sdwa v[220:221], v27 src0_sel:WORD_1
	v_pk_fma_f32 v[210:211], v[156:157], v[218:219], v[210:211] op_sel_hi:[0,1,1]
	v_pk_fma_f32 v[212:213], v[156:157], v[220:221], v[212:213] op_sel_hi:[0,1,1]
	s_waitcnt vmcnt(28)
	v_cvt_pk_f32_fp8_e32 v[214:215], v28
	v_cvt_pk_f32_fp8_sdwa v[216:217], v28 src0_sel:WORD_1
	v_pk_fma_f32 v[198:199], v[156:157], v[214:215], v[198:199] op_sel:[1,0,0]
	v_pk_fma_f32 v[200:201], v[156:157], v[216:217], v[200:201] op_sel:[1,0,0]
	v_cvt_pk_f32_fp8_e32 v[218:219], v29
	v_cvt_pk_f32_fp8_sdwa v[220:221], v29 src0_sel:WORD_1
	v_pk_fma_f32 v[202:203], v[156:157], v[218:219], v[202:203] op_sel:[1,0,0]
	v_pk_fma_f32 v[204:205], v[156:157], v[220:221], v[204:205] op_sel:[1,0,0]
	v_cvt_pk_f32_fp8_e32 v[214:215], v30
	v_cvt_pk_f32_fp8_sdwa v[216:217], v30 src0_sel:WORD_1
	v_pk_fma_f32 v[206:207], v[156:157], v[214:215], v[206:207] op_sel:[1,0,0]
	v_pk_fma_f32 v[208:209], v[156:157], v[216:217], v[208:209] op_sel:[1,0,0]
	v_cvt_pk_f32_fp8_e32 v[218:219], v31
	v_cvt_pk_f32_fp8_sdwa v[220:221], v31 src0_sel:WORD_1
	v_pk_fma_f32 v[210:211], v[156:157], v[218:219], v[210:211] op_sel:[1,0,0]
	v_pk_fma_f32 v[212:213], v[156:157], v[220:221], v[212:213] op_sel:[1,0,0]
	ds_read_b128 v[154:157], v139 offset:16
	s_waitcnt vmcnt(27)
	v_cvt_pk_f32_fp8_e32 v[214:215], v32
	v_cvt_pk_f32_fp8_sdwa v[216:217], v32 src0_sel:WORD_1
	v_pk_fma_f32 v[198:199], v[158:159], v[214:215], v[198:199] op_sel_hi:[0,1,1]
	v_pk_fma_f32 v[200:201], v[158:159], v[216:217], v[200:201] op_sel_hi:[0,1,1]
	v_cvt_pk_f32_fp8_e32 v[218:219], v33
	v_cvt_pk_f32_fp8_sdwa v[220:221], v33 src0_sel:WORD_1
	v_pk_fma_f32 v[202:203], v[158:159], v[218:219], v[202:203] op_sel_hi:[0,1,1]
	v_pk_fma_f32 v[204:205], v[158:159], v[220:221], v[204:205] op_sel_hi:[0,1,1]
	v_cvt_pk_f32_fp8_e32 v[214:215], v34
	v_cvt_pk_f32_fp8_sdwa v[216:217], v34 src0_sel:WORD_1
	v_pk_fma_f32 v[206:207], v[158:159], v[214:215], v[206:207] op_sel_hi:[0,1,1]
	v_pk_fma_f32 v[208:209], v[158:159], v[216:217], v[208:209] op_sel_hi:[0,1,1]
	v_cvt_pk_f32_fp8_e32 v[218:219], v35
	v_cvt_pk_f32_fp8_sdwa v[220:221], v35 src0_sel:WORD_1
	v_pk_fma_f32 v[210:211], v[158:159], v[218:219], v[210:211] op_sel_hi:[0,1,1]
	v_pk_fma_f32 v[212:213], v[158:159], v[220:221], v[212:213] op_sel_hi:[0,1,1]
	s_waitcnt vmcnt(26)
	v_cvt_pk_f32_fp8_e32 v[214:215], v36
	v_cvt_pk_f32_fp8_sdwa v[216:217], v36 src0_sel:WORD_1
	v_pk_fma_f32 v[198:199], v[158:159], v[214:215], v[198:199] op_sel:[1,0,0]
	v_pk_fma_f32 v[200:201], v[158:159], v[216:217], v[200:201] op_sel:[1,0,0]
	v_cvt_pk_f32_fp8_e32 v[218:219], v37
	v_cvt_pk_f32_fp8_sdwa v[220:221], v37 src0_sel:WORD_1
	v_pk_fma_f32 v[202:203], v[158:159], v[218:219], v[202:203] op_sel:[1,0,0]
	v_pk_fma_f32 v[204:205], v[158:159], v[220:221], v[204:205] op_sel:[1,0,0]
	v_cvt_pk_f32_fp8_e32 v[214:215], v38
	v_cvt_pk_f32_fp8_sdwa v[216:217], v38 src0_sel:WORD_1
	v_pk_fma_f32 v[206:207], v[158:159], v[214:215], v[206:207] op_sel:[1,0,0]
	v_pk_fma_f32 v[208:209], v[158:159], v[216:217], v[208:209] op_sel:[1,0,0]
	v_cvt_pk_f32_fp8_e32 v[218:219], v39
	v_cvt_pk_f32_fp8_sdwa v[220:221], v39 src0_sel:WORD_1
	v_pk_fma_f32 v[210:211], v[158:159], v[218:219], v[210:211] op_sel:[1,0,0]
	v_pk_fma_f32 v[212:213], v[158:159], v[220:221], v[212:213] op_sel:[1,0,0]
	s_waitcnt lgkmcnt(0)
	v_lshl_add_u32 v154, v154, 8, v138
	v_lshl_add_u32 v155, v155, 8, v138
	v_lshl_add_u32 v156, v156, 8, v138
	v_lshl_add_u32 v157, v157, 8, v138
	buffer_load_dwordx4 v[16:19], v154, s[16:19], s26 offen
	buffer_load_dwordx4 v[20:23], v155, s[16:19], s26 offen
	buffer_load_dwordx4 v[24:27], v156, s[16:19], s26 offen
	buffer_load_dwordx4 v[28:31], v157, s[16:19], s26 offen
	s_waitcnt vmcnt(29)
	v_cvt_pk_f32_fp8_e32 v[214:215], v40
	v_cvt_pk_f32_fp8_sdwa v[216:217], v40 src0_sel:WORD_1
	v_pk_fma_f32 v[198:199], v[160:161], v[214:215], v[198:199] op_sel_hi:[0,1,1]
	v_pk_fma_f32 v[200:201], v[160:161], v[216:217], v[200:201] op_sel_hi:[0,1,1]
	v_cvt_pk_f32_fp8_e32 v[218:219], v41
	v_cvt_pk_f32_fp8_sdwa v[220:221], v41 src0_sel:WORD_1
	v_pk_fma_f32 v[202:203], v[160:161], v[218:219], v[202:203] op_sel_hi:[0,1,1]
	v_pk_fma_f32 v[204:205], v[160:161], v[220:221], v[204:205] op_sel_hi:[0,1,1]
	v_cvt_pk_f32_fp8_e32 v[214:215], v42
	v_cvt_pk_f32_fp8_sdwa v[216:217], v42 src0_sel:WORD_1
	v_pk_fma_f32 v[206:207], v[160:161], v[214:215], v[206:207] op_sel_hi:[0,1,1]
	v_pk_fma_f32 v[208:209], v[160:161], v[216:217], v[208:209] op_sel_hi:[0,1,1]
	v_cvt_pk_f32_fp8_e32 v[218:219], v43
	v_cvt_pk_f32_fp8_sdwa v[220:221], v43 src0_sel:WORD_1
	v_pk_fma_f32 v[210:211], v[160:161], v[218:219], v[210:211] op_sel_hi:[0,1,1]
	v_pk_fma_f32 v[212:213], v[160:161], v[220:221], v[212:213] op_sel_hi:[0,1,1]
	s_waitcnt vmcnt(28)
; #define LAS __attribute__((address_space(3)))
; __device__ __forceinline__ void kv8_issue(u32x4 (&buf)[8], __amdgpu_buffer_rsrc_t rs, int voff  , int sbase  , const int (&iv)[4], int b) {
;     const int jj = b >> 3, l0 = (b & 7) * 8;
;     const int ivb = (jj == 0) ? iv[0] : (jj == 1) ? iv[1] : (jj == 2) ? iv[2] : iv[3];
; #pragma unroll
;     for (int u = 0; u < 8; ++u) { const int si = __builtin_amdgcn_readlane(ivb, l0 + u); buf[u] = __builtin_amdgcn_raw_buffer_load_b128(rs, voff, si * 2048 + sbase, KV8_AUX); }
; }
; __device__ __forceinline__ void kv8_pv(const u32x4 (&buf)[8], f32x2v (&o2)[8], const LAS float* srow, int b) {
;     const LAS f32x4* p4 = (const LAS f32x4*)(srow + b * 8);
;     const f32x4 p0 = p4[0], p1 = p4[1];
;     const float p[8] = {p0.x, p0.y, p0.z, p0.w, p1.x, p1.y, p1.z, p1.w};
; #pragma unroll
;     for (int u = 0; u < 8; ++u) {
;         const u32x4 v = buf[u]; const f32x2v pp = {p[u], p[u]};
;         o2[0] = __builtin_elementwise_fma(pp, __builtin_amdgcn_cvt_pk_f32_fp8(v.x, false), o2[0]); o2[1] = __builtin_elementwise_fma(pp, __builtin_amdgcn_cvt_pk_f32_fp8(v.x, true), o2[1]);
;         o2[2] = __builtin_elementwise_fma(pp, __builtin_amdgcn_cvt_pk_f32_fp8(v.y, false), o2[2]); o2[3] = __builtin_elementwise_fma(pp, __builtin_amdgcn_cvt_pk_f32_fp8(v.y, true), o2[3]);
;         o2[4] = __builtin_elementwise_fma(pp, __builtin_amdgcn_cvt_pk_f32_fp8(v.z, false), o2[4]); o2[5] = __builtin_elementwise_fma(pp, __builtin_amdgcn_cvt_pk_f32_fp8(v.z, true), o2[5]);
;         o2[6] = __builtin_elementwise_fma(pp, __builtin_amdgcn_cvt_pk_f32_fp8(v.w, false), o2[6]); o2[7] = __builtin_elementwise_fma(pp, __builtin_amdgcn_cvt_pk_f32_fp8(v.w, true), o2[7]);
;     }
	v_cvt_pk_f32_fp8_e32 v[214:215], v44
	v_cvt_pk_f32_fp8_sdwa v[216:217], v44 src0_sel:WORD_1
	v_pk_fma_f32 v[198:199], v[160:161], v[214:215], v[198:199] op_sel:[1,0,0]
	v_pk_fma_f32 v[200:201], v[160:161], v[216:217], v[200:201] op_sel:[1,0,0]
	v_cvt_pk_f32_fp8_e32 v[218:219], v45
	v_cvt_pk_f32_fp8_sdwa v[220:221], v45 src0_sel:WORD_1
	v_pk_fma_f32 v[202:203], v[160:161], v[218:219], v[202:203] op_sel:[1,0,0]
	v_pk_fma_f32 v[204:205], v[160:161], v[220:221], v[204:205] op_sel:[1,0,0]
	v_cvt_pk_f32_fp8_e32 v[214:215], v46
	v_cvt_pk_f32_fp8_sdwa v[216:217], v46 src0_sel:WORD_1
	v_pk_fma_f32 v[206:207], v[160:161], v[214:215], v[206:207] op_sel:[1,0,0]
	v_pk_fma_f32 v[208:209], v[160:161], v[216:217], v[208:209] op_sel:[1,0,0]
	v_cvt_pk_f32_fp8_e32 v[218:219], v47
	v_cvt_pk_f32_fp8_sdwa v[220:221], v47 src0_sel:WORD_1
	v_pk_fma_f32 v[210:211], v[160:161], v[218:219], v[210:211] op_sel:[1,0,0]
	v_pk_fma_f32 v[212:213], v[160:161], v[220:221], v[212:213] op_sel:[1,0,0]
	ds_read_b128 v[158:161], v139 offset:32
	s_waitcnt vmcnt(27)
	v_cvt_pk_f32_fp8_e32 v[214:215], v48
	v_cvt_pk_f32_fp8_sdwa v[216:217], v48 src0_sel:WORD_1
	v_pk_fma_f32 v[198:199], v[162:163], v[214:215], v[198:199] op_sel_hi:[0,1,1]
	v_pk_fma_f32 v[200:201], v[162:163], v[216:217], v[200:201] op_sel_hi:[0,1,1]
	v_cvt_pk_f32_fp8_e32 v[218:219], v49
	v_cvt_pk_f32_fp8_sdwa v[220:221], v49 src0_sel:WORD_1
	v_pk_fma_f32 v[202:203], v[162:163], v[218:219], v[202:203] op_sel_hi:[0,1,1]
	v_pk_fma_f32 v[204:205], v[162:163], v[220:221], v[204:205] op_sel_hi:[0,1,1]
	v_cvt_pk_f32_fp8_e32 v[214:215], v50
	v_cvt_pk_f32_fp8_sdwa v[216:217], v50 src0_sel:WORD_1
	v_pk_fma_f32 v[206:207], v[162:163], v[214:215], v[206:207] op_sel_hi:[0,1,1]
	v_pk_fma_f32 v[208:209], v[162:163], v[216:217], v[208:209] op_sel_hi:[0,1,1]
	v_cvt_pk_f32_fp8_e32 v[218:219], v51
	v_cvt_pk_f32_fp8_sdwa v[220:221], v51 src0_sel:WORD_1
	v_pk_fma_f32 v[210:211], v[162:163], v[218:219], v[210:211] op_sel_hi:[0,1,1]
	v_pk_fma_f32 v[212:213], v[162:163], v[220:221], v[212:213] op_sel_hi:[0,1,1]
	s_waitcnt vmcnt(26)
	v_cvt_pk_f32_fp8_e32 v[214:215], v52
	v_cvt_pk_f32_fp8_sdwa v[216:217], v52 src0_sel:WORD_1
	v_pk_fma_f32 v[198:199], v[162:163], v[214:215], v[198:199] op_sel:[1,0,0]
	v_pk_fma_f32 v[200:201], v[162:163], v[216:217], v[200:201] op_sel:[1,0,0]
	v_cvt_pk_f32_fp8_e32 v[218:219], v53
	v_cvt_pk_f32_fp8_sdwa v[220:221], v53 src0_sel:WORD_1
	v_pk_fma_f32 v[202:203], v[162:163], v[218:219], v[202:203] op_sel:[1,0,0]
	v_pk_fma_f32 v[204:205], v[162:163], v[220:221], v[204:205] op_sel:[1,0,0]
	v_cvt_pk_f32_fp8_e32 v[214:215], v54
	v_cvt_pk_f32_fp8_sdwa v[216:217], v54 src0_sel:WORD_1
	v_pk_fma_f32 v[206:207], v[162:163], v[214:215], v[206:207] op_sel:[1,0,0]
	v_pk_fma_f32 v[208:209], v[162:163], v[216:217], v[208:209] op_sel:[1,0,0]
	v_cvt_pk_f32_fp8_e32 v[218:219], v55
	v_cvt_pk_f32_fp8_sdwa v[220:221], v55 src0_sel:WORD_1
	v_pk_fma_f32 v[210:211], v[162:163], v[218:219], v[210:211] op_sel:[1,0,0]
	v_pk_fma_f32 v[212:213], v[162:163], v[220:221], v[212:213] op_sel:[1,0,0]
	s_waitcnt lgkmcnt(0)
	v_lshl_add_u32 v158, v158, 8, v138
	v_lshl_add_u32 v159, v159, 8, v138
	v_lshl_add_u32 v160, v160, 8, v138
	v_lshl_add_u32 v161, v161, 8, v138
	buffer_load_dwordx4 v[32:35], v158, s[16:19], s26 offen
	buffer_load_dwordx4 v[36:39], v159, s[16:19], s26 offen
	buffer_load_dwordx4 v[40:43], v160, s[16:19], s26 offen
	buffer_load_dwordx4 v[44:47], v161, s[16:19], s26 offen
	s_waitcnt vmcnt(29)
	v_cvt_pk_f32_fp8_e32 v[214:215], v56
	v_cvt_pk_f32_fp8_sdwa v[216:217], v56 src0_sel:WORD_1
	v_pk_fma_f32 v[198:199], v[164:165], v[214:215], v[198:199] op_sel_hi:[0,1,1]
	v_pk_fma_f32 v[200:201], v[164:165], v[216:217], v[200:201] op_sel_hi:[0,1,1]
	v_cvt_pk_f32_fp8_e32 v[218:219], v57
	v_cvt_pk_f32_fp8_sdwa v[220:221], v57 src0_sel:WORD_1
	v_pk_fma_f32 v[202:203], v[164:165], v[218:219], v[202:203] op_sel_hi:[0,1,1]
	v_pk_fma_f32 v[204:205], v[164:165], v[220:221], v[204:205] op_sel_hi:[0,1,1]
	v_cvt_pk_f32_fp8_e32 v[214:215], v58
	v_cvt_pk_f32_fp8_sdwa v[216:217], v58 src0_sel:WORD_1
	v_pk_fma_f32 v[206:207], v[164:165], v[214:215], v[206:207] op_sel_hi:[0,1,1]
	v_pk_fma_f32 v[208:209], v[164:165], v[216:217], v[208:209] op_sel_hi:[0,1,1]
	v_cvt_pk_f32_fp8_e32 v[218:219], v59
	v_cvt_pk_f32_fp8_sdwa v[220:221], v59 src0_sel:WORD_1
	v_pk_fma_f32 v[210:211], v[164:165], v[218:219], v[210:211] op_sel_hi:[0,1,1]
	v_pk_fma_f32 v[212:213], v[164:165], v[220:221], v[212:213] op_sel_hi:[0,1,1]
	s_waitcnt vmcnt(28)
	v_cvt_pk_f32_fp8_e32 v[214:215], v60
	v_cvt_pk_f32_fp8_sdwa v[216:217], v60 src0_sel:WORD_1
	v_pk_fma_f32 v[198:199], v[164:165], v[214:215], v[198:199] op_sel:[1,0,0]
	v_pk_fma_f32 v[200:201], v[164:165], v[216:217], v[200:201] op_sel:[1,0,0]
	v_cvt_pk_f32_fp8_e32 v[218:219], v61
	v_cvt_pk_f32_fp8_sdwa v[220:221], v61 src0_sel:WORD_1
	v_pk_fma_f32 v[202:203], v[164:165], v[218:219], v[202:203] op_sel:[1,0,0]
	v_pk_fma_f32 v[204:205], v[164:165], v[220:221], v[204:205] op_sel:[1,0,0]
	v_cvt_pk_f32_fp8_e32 v[214:215], v62
	v_cvt_pk_f32_fp8_sdwa v[216:217], v62 src0_sel:WORD_1
	v_pk_fma_f32 v[206:207], v[164:165], v[214:215], v[206:207] op_sel:[1,0,0]
	v_pk_fma_f32 v[208:209], v[164:165], v[216:217], v[208:209] op_sel:[1,0,0]
	v_cvt_pk_f32_fp8_e32 v[218:219], v63
	v_cvt_pk_f32_fp8_sdwa v[220:221], v63 src0_sel:WORD_1
	v_pk_fma_f32 v[210:211], v[164:165], v[218:219], v[210:211] op_sel:[1,0,0]
	v_pk_fma_f32 v[212:213], v[164:165], v[220:221], v[212:213] op_sel:[1,0,0]
	ds_read_b128 v[162:165], v139 offset:48
	s_waitcnt vmcnt(27)
; #define LAS __attribute__((address_space(3)))
; __device__ __forceinline__ void kv8_issue(u32x4 (&buf)[8], __amdgpu_buffer_rsrc_t rs, int voff  , int sbase  , const int (&iv)[4], int b) {
;     const int jj = b >> 3, l0 = (b & 7) * 8;
;     const int ivb = (jj == 0) ? iv[0] : (jj == 1) ? iv[1] : (jj == 2) ? iv[2] : iv[3];
; #pragma unroll
;     for (int u = 0; u < 8; ++u) { const int si = __builtin_amdgcn_readlane(ivb, l0 + u); buf[u] = __builtin_amdgcn_raw_buffer_load_b128(rs, voff, si * 2048 + sbase, KV8_AUX); }
; }
; __device__ __forceinline__ void kv8_pv(const u32x4 (&buf)[8], f32x2v (&o2)[8], const LAS float* srow, int b) {
;     const LAS f32x4* p4 = (const LAS f32x4*)(srow + b * 8);
;     const f32x4 p0 = p4[0], p1 = p4[1];
;     const float p[8] = {p0.x, p0.y, p0.z, p0.w, p1.x, p1.y, p1.z, p1.w};
; #pragma unroll
;     for (int u = 0; u < 8; ++u) {
;         const u32x4 v = buf[u]; const f32x2v pp = {p[u], p[u]};
;         o2[0] = __builtin_elementwise_fma(pp, __builtin_amdgcn_cvt_pk_f32_fp8(v.x, false), o2[0]); o2[1] = __builtin_elementwise_fma(pp, __builtin_amdgcn_cvt_pk_f32_fp8(v.x, true), o2[1]);
;         o2[2] = __builtin_elementwise_fma(pp, __builtin_amdgcn_cvt_pk_f32_fp8(v.y, false), o2[2]); o2[3] = __builtin_elementwise_fma(pp, __builtin_amdgcn_cvt_pk_f32_fp8(v.y, true), o2[3]);
;         o2[4] = __builtin_elementwise_fma(pp, __builtin_amdgcn_cvt_pk_f32_fp8(v.z, false), o2[4]); o2[5] = __builtin_elementwise_fma(pp, __builtin_amdgcn_cvt_pk_f32_fp8(v.z, true), o2[5]);
;         o2[6] = __builtin_elementwise_fma(pp, __builtin_amdgcn_cvt_pk_f32_fp8(v.w, false), o2[6]); o2[7] = __builtin_elementwise_fma(pp, __builtin_amdgcn_cvt_pk_f32_fp8(v.w, true), o2[7]);
;     }
	v_cvt_pk_f32_fp8_e32 v[214:215], v64
	v_cvt_pk_f32_fp8_sdwa v[216:217], v64 src0_sel:WORD_1
	v_pk_fma_f32 v[198:199], v[166:167], v[214:215], v[198:199] op_sel_hi:[0,1,1]
	v_pk_fma_f32 v[200:201], v[166:167], v[216:217], v[200:201] op_sel_hi:[0,1,1]
	v_cvt_pk_f32_fp8_e32 v[218:219], v65
	v_cvt_pk_f32_fp8_sdwa v[220:221], v65 src0_sel:WORD_1
	v_pk_fma_f32 v[202:203], v[166:167], v[218:219], v[202:203] op_sel_hi:[0,1,1]
	v_pk_fma_f32 v[204:205], v[166:167], v[220:221], v[204:205] op_sel_hi:[0,1,1]
	v_cvt_pk_f32_fp8_e32 v[214:215], v66
	v_cvt_pk_f32_fp8_sdwa v[216:217], v66 src0_sel:WORD_1
	v_pk_fma_f32 v[206:207], v[166:167], v[214:215], v[206:207] op_sel_hi:[0,1,1]
	v_pk_fma_f32 v[208:209], v[166:167], v[216:217], v[208:209] op_sel_hi:[0,1,1]
	v_cvt_pk_f32_fp8_e32 v[218:219], v67
	v_cvt_pk_f32_fp8_sdwa v[220:221], v67 src0_sel:WORD_1
	v_pk_fma_f32 v[210:211], v[166:167], v[218:219], v[210:211] op_sel_hi:[0,1,1]
	v_pk_fma_f32 v[212:213], v[166:167], v[220:221], v[212:213] op_sel_hi:[0,1,1]
	s_waitcnt vmcnt(26)
	v_cvt_pk_f32_fp8_e32 v[214:215], v68
	v_cvt_pk_f32_fp8_sdwa v[216:217], v68 src0_sel:WORD_1
	v_pk_fma_f32 v[198:199], v[166:167], v[214:215], v[198:199] op_sel:[1,0,0]
	v_pk_fma_f32 v[200:201], v[166:167], v[216:217], v[200:201] op_sel:[1,0,0]
	v_cvt_pk_f32_fp8_e32 v[218:219], v69
	v_cvt_pk_f32_fp8_sdwa v[220:221], v69 src0_sel:WORD_1
	v_pk_fma_f32 v[202:203], v[166:167], v[218:219], v[202:203] op_sel:[1,0,0]
	v_pk_fma_f32 v[204:205], v[166:167], v[220:221], v[204:205] op_sel:[1,0,0]
	v_cvt_pk_f32_fp8_e32 v[214:215], v70
	v_cvt_pk_f32_fp8_sdwa v[216:217], v70 src0_sel:WORD_1
	v_pk_fma_f32 v[206:207], v[166:167], v[214:215], v[206:207] op_sel:[1,0,0]
	v_pk_fma_f32 v[208:209], v[166:167], v[216:217], v[208:209] op_sel:[1,0,0]
	v_cvt_pk_f32_fp8_e32 v[218:219], v71
	v_cvt_pk_f32_fp8_sdwa v[220:221], v71 src0_sel:WORD_1
	v_pk_fma_f32 v[210:211], v[166:167], v[218:219], v[210:211] op_sel:[1,0,0]
	v_pk_fma_f32 v[212:213], v[166:167], v[220:221], v[212:213] op_sel:[1,0,0]
	s_waitcnt lgkmcnt(0)
	v_lshl_add_u32 v162, v162, 8, v138
	v_lshl_add_u32 v163, v163, 8, v138
	v_lshl_add_u32 v164, v164, 8, v138
	v_lshl_add_u32 v165, v165, 8, v138
	buffer_load_dwordx4 v[48:51], v162, s[16:19], s26 offen
	buffer_load_dwordx4 v[52:55], v163, s[16:19], s26 offen
	buffer_load_dwordx4 v[56:59], v164, s[16:19], s26 offen
	buffer_load_dwordx4 v[60:63], v165, s[16:19], s26 offen
	s_waitcnt vmcnt(29)
	v_cvt_pk_f32_fp8_e32 v[214:215], v72
	v_cvt_pk_f32_fp8_sdwa v[216:217], v72 src0_sel:WORD_1
	v_pk_fma_f32 v[198:199], v[168:169], v[214:215], v[198:199] op_sel_hi:[0,1,1]
	v_pk_fma_f32 v[200:201], v[168:169], v[216:217], v[200:201] op_sel_hi:[0,1,1]
	v_cvt_pk_f32_fp8_e32 v[218:219], v73
	v_cvt_pk_f32_fp8_sdwa v[220:221], v73 src0_sel:WORD_1
	v_pk_fma_f32 v[202:203], v[168:169], v[218:219], v[202:203] op_sel_hi:[0,1,1]
	v_pk_fma_f32 v[204:205], v[168:169], v[220:221], v[204:205] op_sel_hi:[0,1,1]
	v_cvt_pk_f32_fp8_e32 v[214:215], v74
	v_cvt_pk_f32_fp8_sdwa v[216:217], v74 src0_sel:WORD_1
	v_pk_fma_f32 v[206:207], v[168:169], v[214:215], v[206:207] op_sel_hi:[0,1,1]
	v_pk_fma_f32 v[208:209], v[168:169], v[216:217], v[208:209] op_sel_hi:[0,1,1]
	v_cvt_pk_f32_fp8_e32 v[218:219], v75
	v_cvt_pk_f32_fp8_sdwa v[220:221], v75 src0_sel:WORD_1
	v_pk_fma_f32 v[210:211], v[168:169], v[218:219], v[210:211] op_sel_hi:[0,1,1]
	v_pk_fma_f32 v[212:213], v[168:169], v[220:221], v[212:213] op_sel_hi:[0,1,1]
	s_waitcnt vmcnt(28)
	v_cvt_pk_f32_fp8_e32 v[214:215], v76
	v_cvt_pk_f32_fp8_sdwa v[216:217], v76 src0_sel:WORD_1
	v_pk_fma_f32 v[198:199], v[168:169], v[214:215], v[198:199] op_sel:[1,0,0]
	v_pk_fma_f32 v[200:201], v[168:169], v[216:217], v[200:201] op_sel:[1,0,0]
	v_cvt_pk_f32_fp8_e32 v[218:219], v77
	v_cvt_pk_f32_fp8_sdwa v[220:221], v77 src0_sel:WORD_1
	v_pk_fma_f32 v[202:203], v[168:169], v[218:219], v[202:203] op_sel:[1,0,0]
	v_pk_fma_f32 v[204:205], v[168:169], v[220:221], v[204:205] op_sel:[1,0,0]
	v_cvt_pk_f32_fp8_e32 v[214:215], v78
	v_cvt_pk_f32_fp8_sdwa v[216:217], v78 src0_sel:WORD_1
	v_pk_fma_f32 v[206:207], v[168:169], v[214:215], v[206:207] op_sel:[1,0,0]
	v_pk_fma_f32 v[208:209], v[168:169], v[216:217], v[208:209] op_sel:[1,0,0]
	v_cvt_pk_f32_fp8_e32 v[218:219], v79
	v_cvt_pk_f32_fp8_sdwa v[220:221], v79 src0_sel:WORD_1
	v_pk_fma_f32 v[210:211], v[168:169], v[218:219], v[210:211] op_sel:[1,0,0]
	v_pk_fma_f32 v[212:213], v[168:169], v[220:221], v[212:213] op_sel:[1,0,0]
	ds_read_b128 v[166:169], v139 offset:64
	s_waitcnt vmcnt(27)
	v_cvt_pk_f32_fp8_e32 v[214:215], v80
	v_cvt_pk_f32_fp8_sdwa v[216:217], v80 src0_sel:WORD_1
	v_pk_fma_f32 v[198:199], v[170:171], v[214:215], v[198:199] op_sel_hi:[0,1,1]
	v_pk_fma_f32 v[200:201], v[170:171], v[216:217], v[200:201] op_sel_hi:[0,1,1]
	v_cvt_pk_f32_fp8_e32 v[218:219], v81
	v_cvt_pk_f32_fp8_sdwa v[220:221], v81 src0_sel:WORD_1
	v_pk_fma_f32 v[202:203], v[170:171], v[218:219], v[202:203] op_sel_hi:[0,1,1]
	v_pk_fma_f32 v[204:205], v[170:171], v[220:221], v[204:205] op_sel_hi:[0,1,1]
	v_cvt_pk_f32_fp8_e32 v[214:215], v82
	v_cvt_pk_f32_fp8_sdwa v[216:217], v82 src0_sel:WORD_1
	v_pk_fma_f32 v[206:207], v[170:171], v[214:215], v[206:207] op_sel_hi:[0,1,1]
	v_pk_fma_f32 v[208:209], v[170:171], v[216:217], v[208:209] op_sel_hi:[0,1,1]
	v_cvt_pk_f32_fp8_e32 v[218:219], v83
	v_cvt_pk_f32_fp8_sdwa v[220:221], v83 src0_sel:WORD_1
	v_pk_fma_f32 v[210:211], v[170:171], v[218:219], v[210:211] op_sel_hi:[0,1,1]
	v_pk_fma_f32 v[212:213], v[170:171], v[220:221], v[212:213] op_sel_hi:[0,1,1]
	s_waitcnt vmcnt(26)
; #define LAS __attribute__((address_space(3)))
; __device__ __forceinline__ void kv8_issue(u32x4 (&buf)[8], __amdgpu_buffer_rsrc_t rs, int voff  , int sbase  , const int (&iv)[4], int b) {
;     const int jj = b >> 3, l0 = (b & 7) * 8;
;     const int ivb = (jj == 0) ? iv[0] : (jj == 1) ? iv[1] : (jj == 2) ? iv[2] : iv[3];
; #pragma unroll
;     for (int u = 0; u < 8; ++u) { const int si = __builtin_amdgcn_readlane(ivb, l0 + u); buf[u] = __builtin_amdgcn_raw_buffer_load_b128(rs, voff, si * 2048 + sbase, KV8_AUX); }
; }
; __device__ __forceinline__ void kv8_pv(const u32x4 (&buf)[8], f32x2v (&o2)[8], const LAS float* srow, int b) {
;     const LAS f32x4* p4 = (const LAS f32x4*)(srow + b * 8);
;     const f32x4 p0 = p4[0], p1 = p4[1];
;     const float p[8] = {p0.x, p0.y, p0.z, p0.w, p1.x, p1.y, p1.z, p1.w};
; #pragma unroll
;     for (int u = 0; u < 8; ++u) {
;         const u32x4 v = buf[u]; const f32x2v pp = {p[u], p[u]};
;         o2[0] = __builtin_elementwise_fma(pp, __builtin_amdgcn_cvt_pk_f32_fp8(v.x, false), o2[0]); o2[1] = __builtin_elementwise_fma(pp, __builtin_amdgcn_cvt_pk_f32_fp8(v.x, true), o2[1]);
;         o2[2] = __builtin_elementwise_fma(pp, __builtin_amdgcn_cvt_pk_f32_fp8(v.y, false), o2[2]); o2[3] = __builtin_elementwise_fma(pp, __builtin_amdgcn_cvt_pk_f32_fp8(v.y, true), o2[3]);
;         o2[4] = __builtin_elementwise_fma(pp, __builtin_amdgcn_cvt_pk_f32_fp8(v.z, false), o2[4]); o2[5] = __builtin_elementwise_fma(pp, __builtin_amdgcn_cvt_pk_f32_fp8(v.z, true), o2[5]);
;         o2[6] = __builtin_elementwise_fma(pp, __builtin_amdgcn_cvt_pk_f32_fp8(v.w, false), o2[6]); o2[7] = __builtin_elementwise_fma(pp, __builtin_amdgcn_cvt_pk_f32_fp8(v.w, true), o2[7]);
;     }
	v_cvt_pk_f32_fp8_e32 v[214:215], v84
	v_cvt_pk_f32_fp8_sdwa v[216:217], v84 src0_sel:WORD_1
	v_pk_fma_f32 v[198:199], v[170:171], v[214:215], v[198:199] op_sel:[1,0,0]
	v_pk_fma_f32 v[200:201], v[170:171], v[216:217], v[200:201] op_sel:[1,0,0]
	v_cvt_pk_f32_fp8_e32 v[218:219], v85
	v_cvt_pk_f32_fp8_sdwa v[220:221], v85 src0_sel:WORD_1
	v_pk_fma_f32 v[202:203], v[170:171], v[218:219], v[202:203] op_sel:[1,0,0]
	v_pk_fma_f32 v[204:205], v[170:171], v[220:221], v[204:205] op_sel:[1,0,0]
	v_cvt_pk_f32_fp8_e32 v[214:215], v86
	v_cvt_pk_f32_fp8_sdwa v[216:217], v86 src0_sel:WORD_1
	v_pk_fma_f32 v[206:207], v[170:171], v[214:215], v[206:207] op_sel:[1,0,0]
	v_pk_fma_f32 v[208:209], v[170:171], v[216:217], v[208:209] op_sel:[1,0,0]
	v_cvt_pk_f32_fp8_e32 v[218:219], v87
	v_cvt_pk_f32_fp8_sdwa v[220:221], v87 src0_sel:WORD_1
	v_pk_fma_f32 v[210:211], v[170:171], v[218:219], v[210:211] op_sel:[1,0,0]
	v_pk_fma_f32 v[212:213], v[170:171], v[220:221], v[212:213] op_sel:[1,0,0]
	s_waitcnt lgkmcnt(0)
	v_lshl_add_u32 v166, v166, 8, v138
	v_lshl_add_u32 v167, v167, 8, v138
	v_lshl_add_u32 v168, v168, 8, v138
	v_lshl_add_u32 v169, v169, 8, v138
	buffer_load_dwordx4 v[64:67], v166, s[16:19], s26 offen
	buffer_load_dwordx4 v[68:71], v167, s[16:19], s26 offen
	buffer_load_dwordx4 v[72:75], v168, s[16:19], s26 offen
	buffer_load_dwordx4 v[76:79], v169, s[16:19], s26 offen
	s_waitcnt vmcnt(29)
	v_cvt_pk_f32_fp8_e32 v[214:215], v88
	v_cvt_pk_f32_fp8_sdwa v[216:217], v88 src0_sel:WORD_1
	v_pk_fma_f32 v[198:199], v[172:173], v[214:215], v[198:199] op_sel_hi:[0,1,1]
	v_pk_fma_f32 v[200:201], v[172:173], v[216:217], v[200:201] op_sel_hi:[0,1,1]
	v_cvt_pk_f32_fp8_e32 v[218:219], v89
	v_cvt_pk_f32_fp8_sdwa v[220:221], v89 src0_sel:WORD_1
	v_pk_fma_f32 v[202:203], v[172:173], v[218:219], v[202:203] op_sel_hi:[0,1,1]
	v_pk_fma_f32 v[204:205], v[172:173], v[220:221], v[204:205] op_sel_hi:[0,1,1]
	v_cvt_pk_f32_fp8_e32 v[214:215], v90
	v_cvt_pk_f32_fp8_sdwa v[216:217], v90 src0_sel:WORD_1
	v_pk_fma_f32 v[206:207], v[172:173], v[214:215], v[206:207] op_sel_hi:[0,1,1]
	v_pk_fma_f32 v[208:209], v[172:173], v[216:217], v[208:209] op_sel_hi:[0,1,1]
	v_cvt_pk_f32_fp8_e32 v[218:219], v91
	v_cvt_pk_f32_fp8_sdwa v[220:221], v91 src0_sel:WORD_1
	v_pk_fma_f32 v[210:211], v[172:173], v[218:219], v[210:211] op_sel_hi:[0,1,1]
	v_pk_fma_f32 v[212:213], v[172:173], v[220:221], v[212:213] op_sel_hi:[0,1,1]
	s_waitcnt vmcnt(28)
	v_cvt_pk_f32_fp8_e32 v[214:215], v92
	v_cvt_pk_f32_fp8_sdwa v[216:217], v92 src0_sel:WORD_1
	v_pk_fma_f32 v[198:199], v[172:173], v[214:215], v[198:199] op_sel:[1,0,0]
	v_pk_fma_f32 v[200:201], v[172:173], v[216:217], v[200:201] op_sel:[1,0,0]
	v_cvt_pk_f32_fp8_e32 v[218:219], v93
	v_cvt_pk_f32_fp8_sdwa v[220:221], v93 src0_sel:WORD_1
	v_pk_fma_f32 v[202:203], v[172:173], v[218:219], v[202:203] op_sel:[1,0,0]
	v_pk_fma_f32 v[204:205], v[172:173], v[220:221], v[204:205] op_sel:[1,0,0]
	v_cvt_pk_f32_fp8_e32 v[214:215], v94
	v_cvt_pk_f32_fp8_sdwa v[216:217], v94 src0_sel:WORD_1
	v_pk_fma_f32 v[206:207], v[172:173], v[214:215], v[206:207] op_sel:[1,0,0]
	v_pk_fma_f32 v[208:209], v[172:173], v[216:217], v[208:209] op_sel:[1,0,0]
	v_cvt_pk_f32_fp8_e32 v[218:219], v95
	v_cvt_pk_f32_fp8_sdwa v[220:221], v95 src0_sel:WORD_1
	v_pk_fma_f32 v[210:211], v[172:173], v[218:219], v[210:211] op_sel:[1,0,0]
	v_pk_fma_f32 v[212:213], v[172:173], v[220:221], v[212:213] op_sel:[1,0,0]
	ds_read_b128 v[170:173], v139 offset:80
	s_waitcnt vmcnt(27)
	v_cvt_pk_f32_fp8_e32 v[214:215], v96
	v_cvt_pk_f32_fp8_sdwa v[216:217], v96 src0_sel:WORD_1
	v_pk_fma_f32 v[198:199], v[174:175], v[214:215], v[198:199] op_sel_hi:[0,1,1]
	v_pk_fma_f32 v[200:201], v[174:175], v[216:217], v[200:201] op_sel_hi:[0,1,1]
	v_cvt_pk_f32_fp8_e32 v[218:219], v97
	v_cvt_pk_f32_fp8_sdwa v[220:221], v97 src0_sel:WORD_1
	v_pk_fma_f32 v[202:203], v[174:175], v[218:219], v[202:203] op_sel_hi:[0,1,1]
	v_pk_fma_f32 v[204:205], v[174:175], v[220:221], v[204:205] op_sel_hi:[0,1,1]
	v_cvt_pk_f32_fp8_e32 v[214:215], v98
	v_cvt_pk_f32_fp8_sdwa v[216:217], v98 src0_sel:WORD_1
	v_pk_fma_f32 v[206:207], v[174:175], v[214:215], v[206:207] op_sel_hi:[0,1,1]
	v_pk_fma_f32 v[208:209], v[174:175], v[216:217], v[208:209] op_sel_hi:[0,1,1]
	v_cvt_pk_f32_fp8_e32 v[218:219], v99
	v_cvt_pk_f32_fp8_sdwa v[220:221], v99 src0_sel:WORD_1
	v_pk_fma_f32 v[210:211], v[174:175], v[218:219], v[210:211] op_sel_hi:[0,1,1]
	v_pk_fma_f32 v[212:213], v[174:175], v[220:221], v[212:213] op_sel_hi:[0,1,1]
	s_waitcnt vmcnt(26)
	v_cvt_pk_f32_fp8_e32 v[214:215], v100
	v_cvt_pk_f32_fp8_sdwa v[216:217], v100 src0_sel:WORD_1
	v_pk_fma_f32 v[198:199], v[174:175], v[214:215], v[198:199] op_sel:[1,0,0]
	v_pk_fma_f32 v[200:201], v[174:175], v[216:217], v[200:201] op_sel:[1,0,0]
	v_cvt_pk_f32_fp8_e32 v[218:219], v101
	v_cvt_pk_f32_fp8_sdwa v[220:221], v101 src0_sel:WORD_1
	v_pk_fma_f32 v[202:203], v[174:175], v[218:219], v[202:203] op_sel:[1,0,0]
	v_pk_fma_f32 v[204:205], v[174:175], v[220:221], v[204:205] op_sel:[1,0,0]
	v_cvt_pk_f32_fp8_e32 v[214:215], v102
	v_cvt_pk_f32_fp8_sdwa v[216:217], v102 src0_sel:WORD_1
	v_pk_fma_f32 v[206:207], v[174:175], v[214:215], v[206:207] op_sel:[1,0,0]
	v_pk_fma_f32 v[208:209], v[174:175], v[216:217], v[208:209] op_sel:[1,0,0]
	v_cvt_pk_f32_fp8_e32 v[218:219], v103
	v_cvt_pk_f32_fp8_sdwa v[220:221], v103 src0_sel:WORD_1
	v_pk_fma_f32 v[210:211], v[174:175], v[218:219], v[210:211] op_sel:[1,0,0]
	v_pk_fma_f32 v[212:213], v[174:175], v[220:221], v[212:213] op_sel:[1,0,0]
	s_waitcnt lgkmcnt(0)
; #define LAS __attribute__((address_space(3)))
; __device__ __forceinline__ void kv8_issue(u32x4 (&buf)[8], __amdgpu_buffer_rsrc_t rs, int voff  , int sbase  , const int (&iv)[4], int b) {
;     const int jj = b >> 3, l0 = (b & 7) * 8;
;     const int ivb = (jj == 0) ? iv[0] : (jj == 1) ? iv[1] : (jj == 2) ? iv[2] : iv[3];
; #pragma unroll
;     for (int u = 0; u < 8; ++u) { const int si = __builtin_amdgcn_readlane(ivb, l0 + u); buf[u] = __builtin_amdgcn_raw_buffer_load_b128(rs, voff, si * 2048 + sbase, KV8_AUX); }
; }
; __device__ __forceinline__ void kv8_pv(const u32x4 (&buf)[8], f32x2v (&o2)[8], const LAS float* srow, int b) {
;     const LAS f32x4* p4 = (const LAS f32x4*)(srow + b * 8);
;     const f32x4 p0 = p4[0], p1 = p4[1];
;     const float p[8] = {p0.x, p0.y, p0.z, p0.w, p1.x, p1.y, p1.z, p1.w};
; #pragma unroll
;     for (int u = 0; u < 8; ++u) {
;         const u32x4 v = buf[u]; const f32x2v pp = {p[u], p[u]};
;         o2[0] = __builtin_elementwise_fma(pp, __builtin_amdgcn_cvt_pk_f32_fp8(v.x, false), o2[0]); o2[1] = __builtin_elementwise_fma(pp, __builtin_amdgcn_cvt_pk_f32_fp8(v.x, true), o2[1]);
;         o2[2] = __builtin_elementwise_fma(pp, __builtin_amdgcn_cvt_pk_f32_fp8(v.y, false), o2[2]); o2[3] = __builtin_elementwise_fma(pp, __builtin_amdgcn_cvt_pk_f32_fp8(v.y, true), o2[3]);
;         o2[4] = __builtin_elementwise_fma(pp, __builtin_amdgcn_cvt_pk_f32_fp8(v.z, false), o2[4]); o2[5] = __builtin_elementwise_fma(pp, __builtin_amdgcn_cvt_pk_f32_fp8(v.z, true), o2[5]);
;         o2[6] = __builtin_elementwise_fma(pp, __builtin_amdgcn_cvt_pk_f32_fp8(v.w, false), o2[6]); o2[7] = __builtin_elementwise_fma(pp, __builtin_amdgcn_cvt_pk_f32_fp8(v.w, true), o2[7]);
;     }
	v_lshl_add_u32 v170, v170, 8, v138
	v_lshl_add_u32 v171, v171, 8, v138
	v_lshl_add_u32 v172, v172, 8, v138
	v_lshl_add_u32 v173, v173, 8, v138
	buffer_load_dwordx4 v[80:83], v170, s[16:19], s26 offen
	buffer_load_dwordx4 v[84:87], v171, s[16:19], s26 offen
	buffer_load_dwordx4 v[88:91], v172, s[16:19], s26 offen
	buffer_load_dwordx4 v[92:95], v173, s[16:19], s26 offen
	s_waitcnt vmcnt(29)
	v_cvt_pk_f32_fp8_e32 v[214:215], v104
	v_cvt_pk_f32_fp8_sdwa v[216:217], v104 src0_sel:WORD_1
	v_pk_fma_f32 v[198:199], v[176:177], v[214:215], v[198:199] op_sel_hi:[0,1,1]
	v_pk_fma_f32 v[200:201], v[176:177], v[216:217], v[200:201] op_sel_hi:[0,1,1]
	v_cvt_pk_f32_fp8_e32 v[218:219], v105
	v_cvt_pk_f32_fp8_sdwa v[220:221], v105 src0_sel:WORD_1
	v_pk_fma_f32 v[202:203], v[176:177], v[218:219], v[202:203] op_sel_hi:[0,1,1]
	v_pk_fma_f32 v[204:205], v[176:177], v[220:221], v[204:205] op_sel_hi:[0,1,1]
	v_cvt_pk_f32_fp8_e32 v[214:215], v106
	v_cvt_pk_f32_fp8_sdwa v[216:217], v106 src0_sel:WORD_1
	v_pk_fma_f32 v[206:207], v[176:177], v[214:215], v[206:207] op_sel_hi:[0,1,1]
	v_pk_fma_f32 v[208:209], v[176:177], v[216:217], v[208:209] op_sel_hi:[0,1,1]
	v_cvt_pk_f32_fp8_e32 v[218:219], v107
	v_cvt_pk_f32_fp8_sdwa v[220:221], v107 src0_sel:WORD_1
	v_pk_fma_f32 v[210:211], v[176:177], v[218:219], v[210:211] op_sel_hi:[0,1,1]
	v_pk_fma_f32 v[212:213], v[176:177], v[220:221], v[212:213] op_sel_hi:[0,1,1]
	s_waitcnt vmcnt(28)
	v_cvt_pk_f32_fp8_e32 v[214:215], v108
	v_cvt_pk_f32_fp8_sdwa v[216:217], v108 src0_sel:WORD_1
	v_pk_fma_f32 v[198:199], v[176:177], v[214:215], v[198:199] op_sel:[1,0,0]
	v_pk_fma_f32 v[200:201], v[176:177], v[216:217], v[200:201] op_sel:[1,0,0]
	v_cvt_pk_f32_fp8_e32 v[218:219], v109
	v_cvt_pk_f32_fp8_sdwa v[220:221], v109 src0_sel:WORD_1
	v_pk_fma_f32 v[202:203], v[176:177], v[218:219], v[202:203] op_sel:[1,0,0]
	v_pk_fma_f32 v[204:205], v[176:177], v[220:221], v[204:205] op_sel:[1,0,0]
	v_cvt_pk_f32_fp8_e32 v[214:215], v110
	v_cvt_pk_f32_fp8_sdwa v[216:217], v110 src0_sel:WORD_1
	v_pk_fma_f32 v[206:207], v[176:177], v[214:215], v[206:207] op_sel:[1,0,0]
	v_pk_fma_f32 v[208:209], v[176:177], v[216:217], v[208:209] op_sel:[1,0,0]
	v_cvt_pk_f32_fp8_e32 v[218:219], v111
	v_cvt_pk_f32_fp8_sdwa v[220:221], v111 src0_sel:WORD_1
	v_pk_fma_f32 v[210:211], v[176:177], v[218:219], v[210:211] op_sel:[1,0,0]
	v_pk_fma_f32 v[212:213], v[176:177], v[220:221], v[212:213] op_sel:[1,0,0]
	ds_read_b128 v[174:177], v139 offset:96
	s_waitcnt vmcnt(27)
	v_cvt_pk_f32_fp8_e32 v[214:215], v112
	v_cvt_pk_f32_fp8_sdwa v[216:217], v112 src0_sel:WORD_1
	v_pk_fma_f32 v[198:199], v[178:179], v[214:215], v[198:199] op_sel_hi:[0,1,1]
	v_pk_fma_f32 v[200:201], v[178:179], v[216:217], v[200:201] op_sel_hi:[0,1,1]
	v_cvt_pk_f32_fp8_e32 v[218:219], v113
	v_cvt_pk_f32_fp8_sdwa v[220:221], v113 src0_sel:WORD_1
	v_pk_fma_f32 v[202:203], v[178:179], v[218:219], v[202:203] op_sel_hi:[0,1,1]
	v_pk_fma_f32 v[204:205], v[178:179], v[220:221], v[204:205] op_sel_hi:[0,1,1]
	v_cvt_pk_f32_fp8_e32 v[214:215], v114
	v_cvt_pk_f32_fp8_sdwa v[216:217], v114 src0_sel:WORD_1
	v_pk_fma_f32 v[206:207], v[178:179], v[214:215], v[206:207] op_sel_hi:[0,1,1]
	v_pk_fma_f32 v[208:209], v[178:179], v[216:217], v[208:209] op_sel_hi:[0,1,1]
	v_cvt_pk_f32_fp8_e32 v[218:219], v115
	v_cvt_pk_f32_fp8_sdwa v[220:221], v115 src0_sel:WORD_1
	v_pk_fma_f32 v[210:211], v[178:179], v[218:219], v[210:211] op_sel_hi:[0,1,1]
	v_pk_fma_f32 v[212:213], v[178:179], v[220:221], v[212:213] op_sel_hi:[0,1,1]
	s_waitcnt vmcnt(26)
	v_cvt_pk_f32_fp8_e32 v[214:215], v116
	v_cvt_pk_f32_fp8_sdwa v[216:217], v116 src0_sel:WORD_1
	v_pk_fma_f32 v[198:199], v[178:179], v[214:215], v[198:199] op_sel:[1,0,0]
	v_pk_fma_f32 v[200:201], v[178:179], v[216:217], v[200:201] op_sel:[1,0,0]
	v_cvt_pk_f32_fp8_e32 v[218:219], v117
	v_cvt_pk_f32_fp8_sdwa v[220:221], v117 src0_sel:WORD_1
	v_pk_fma_f32 v[202:203], v[178:179], v[218:219], v[202:203] op_sel:[1,0,0]
	v_pk_fma_f32 v[204:205], v[178:179], v[220:221], v[204:205] op_sel:[1,0,0]
	v_cvt_pk_f32_fp8_e32 v[214:215], v118
	v_cvt_pk_f32_fp8_sdwa v[216:217], v118 src0_sel:WORD_1
	v_pk_fma_f32 v[206:207], v[178:179], v[214:215], v[206:207] op_sel:[1,0,0]
	v_pk_fma_f32 v[208:209], v[178:179], v[216:217], v[208:209] op_sel:[1,0,0]
	v_cvt_pk_f32_fp8_e32 v[218:219], v119
	v_cvt_pk_f32_fp8_sdwa v[220:221], v119 src0_sel:WORD_1
	v_pk_fma_f32 v[210:211], v[178:179], v[218:219], v[210:211] op_sel:[1,0,0]
	v_pk_fma_f32 v[212:213], v[178:179], v[220:221], v[212:213] op_sel:[1,0,0]
	s_waitcnt lgkmcnt(0)
	v_lshl_add_u32 v174, v174, 8, v138
	v_lshl_add_u32 v175, v175, 8, v138
	v_lshl_add_u32 v176, v176, 8, v138
	v_lshl_add_u32 v177, v177, 8, v138
	buffer_load_dwordx4 v[96:99], v174, s[16:19], s26 offen
	buffer_load_dwordx4 v[100:103], v175, s[16:19], s26 offen
	buffer_load_dwordx4 v[104:107], v176, s[16:19], s26 offen
	buffer_load_dwordx4 v[108:111], v177, s[16:19], s26 offen
	s_waitcnt vmcnt(29)
; __device__ __forceinline__ unsigned cvt_pk_bf16(float lo, float hi) { unsigned r; asm volatile("v_cvt_pk_bf16_f32 %0, %1, %2" : "=v"(r) : "v"(lo), "v"(hi)); return r; }
; #define LAS __attribute__((address_space(3)))
; __device__ __forceinline__ void kv8_pv(const u32x4 (&buf)[8], f32x2v (&o2)[8], const LAS float* srow, int b) {
;     const LAS f32x4* p4 = (const LAS f32x4*)(srow + b * 8);
;     const f32x4 p0 = p4[0], p1 = p4[1];
;     const float p[8] = {p0.x, p0.y, p0.z, p0.w, p1.x, p1.y, p1.z, p1.w};
; #pragma unroll
;     for (int u = 0; u < 8; ++u) {
;         const u32x4 v = buf[u]; const f32x2v pp = {p[u], p[u]};
;         o2[0] = __builtin_elementwise_fma(pp, __builtin_amdgcn_cvt_pk_f32_fp8(v.x, false), o2[0]); o2[1] = __builtin_elementwise_fma(pp, __builtin_amdgcn_cvt_pk_f32_fp8(v.x, true), o2[1]);
;         o2[2] = __builtin_elementwise_fma(pp, __builtin_amdgcn_cvt_pk_f32_fp8(v.y, false), o2[2]); o2[3] = __builtin_elementwise_fma(pp, __builtin_amdgcn_cvt_pk_f32_fp8(v.y, true), o2[3]);
;         o2[4] = __builtin_elementwise_fma(pp, __builtin_amdgcn_cvt_pk_f32_fp8(v.z, false), o2[4]); o2[5] = __builtin_elementwise_fma(pp, __builtin_amdgcn_cvt_pk_f32_fp8(v.z, true), o2[5]);
;         o2[6] = __builtin_elementwise_fma(pp, __builtin_amdgcn_cvt_pk_f32_fp8(v.w, false), o2[6]); o2[7] = __builtin_elementwise_fma(pp, __builtin_amdgcn_cvt_pk_f32_fp8(v.w, true), o2[7]);
;     }
; __device__ __forceinline__ void attn_query8(const unsigned char* __restrict__ KV8, const bf16_t* __restrict__ Z, const int* __restrict__ SEL, bf16_t* __restrict__ YMIX, int t, LAS float* sbuf  ) {
;     ...
;     u32x4 o0, o1;
;     o0.x = cvt_pk_bf16(o[0].x, o[0].y); o0.y = cvt_pk_bf16(o[1].x, o[1].y); o0.z = cvt_pk_bf16(o[2].x, o[2].y); o0.w = cvt_pk_bf16(o[3].x, o[3].y);
;     o1.x = cvt_pk_bf16(o[4].x, o[4].y); o1.y = cvt_pk_bf16(o[5].x, o[5].y); o1.z = cvt_pk_bf16(o[6].x, o[6].y); o1.w = cvt_pk_bf16(o[7].x, o[7].y);
;     u32x4* yp = (u32x4*)(YMIX + (size_t)t * D_ + 1024 + lane * 16);
;     yp[0] = o0; yp[1] = o1;
	v_cvt_pk_f32_fp8_e32 v[214:215], v120
	v_cvt_pk_f32_fp8_sdwa v[216:217], v120 src0_sel:WORD_1
	v_pk_fma_f32 v[198:199], v[180:181], v[214:215], v[198:199] op_sel_hi:[0,1,1]
	v_pk_fma_f32 v[200:201], v[180:181], v[216:217], v[200:201] op_sel_hi:[0,1,1]
	v_cvt_pk_f32_fp8_e32 v[218:219], v121
	v_cvt_pk_f32_fp8_sdwa v[220:221], v121 src0_sel:WORD_1
	v_pk_fma_f32 v[202:203], v[180:181], v[218:219], v[202:203] op_sel_hi:[0,1,1]
	v_pk_fma_f32 v[204:205], v[180:181], v[220:221], v[204:205] op_sel_hi:[0,1,1]
	v_cvt_pk_f32_fp8_e32 v[214:215], v122
	v_cvt_pk_f32_fp8_sdwa v[216:217], v122 src0_sel:WORD_1
	v_pk_fma_f32 v[206:207], v[180:181], v[214:215], v[206:207] op_sel_hi:[0,1,1]
	v_pk_fma_f32 v[208:209], v[180:181], v[216:217], v[208:209] op_sel_hi:[0,1,1]
	v_cvt_pk_f32_fp8_e32 v[218:219], v123
	v_cvt_pk_f32_fp8_sdwa v[220:221], v123 src0_sel:WORD_1
	v_pk_fma_f32 v[210:211], v[180:181], v[218:219], v[210:211] op_sel_hi:[0,1,1]
	v_pk_fma_f32 v[212:213], v[180:181], v[220:221], v[212:213] op_sel_hi:[0,1,1]
	s_waitcnt vmcnt(28)
	v_cvt_pk_f32_fp8_e32 v[214:215], v124
	v_cvt_pk_f32_fp8_sdwa v[216:217], v124 src0_sel:WORD_1
	v_pk_fma_f32 v[198:199], v[180:181], v[214:215], v[198:199] op_sel:[1,0,0]
	v_pk_fma_f32 v[200:201], v[180:181], v[216:217], v[200:201] op_sel:[1,0,0]
	v_cvt_pk_f32_fp8_e32 v[218:219], v125
	v_cvt_pk_f32_fp8_sdwa v[220:221], v125 src0_sel:WORD_1
	v_pk_fma_f32 v[202:203], v[180:181], v[218:219], v[202:203] op_sel:[1,0,0]
	v_pk_fma_f32 v[204:205], v[180:181], v[220:221], v[204:205] op_sel:[1,0,0]
	v_cvt_pk_f32_fp8_e32 v[214:215], v126
	v_cvt_pk_f32_fp8_sdwa v[216:217], v126 src0_sel:WORD_1
	v_pk_fma_f32 v[206:207], v[180:181], v[214:215], v[206:207] op_sel:[1,0,0]
	v_pk_fma_f32 v[208:209], v[180:181], v[216:217], v[208:209] op_sel:[1,0,0]
	v_cvt_pk_f32_fp8_e32 v[218:219], v127
	v_cvt_pk_f32_fp8_sdwa v[220:221], v127 src0_sel:WORD_1
	v_pk_fma_f32 v[210:211], v[180:181], v[218:219], v[210:211] op_sel:[1,0,0]
	v_pk_fma_f32 v[212:213], v[180:181], v[220:221], v[212:213] op_sel:[1,0,0]
	ds_read_b128 v[178:181], v139 offset:112
	v_add_f32_dpp v198, v198, v198 row_ror:8 row_mask:0xf bank_mask:0x3
	v_add_f32_dpp v199, v199, v199 row_ror:8 row_mask:0xf bank_mask:0x3
	v_add_f32_dpp v200, v200, v200 row_ror:8 row_mask:0xf bank_mask:0x3
	v_add_f32_dpp v201, v201, v201 row_ror:8 row_mask:0xf bank_mask:0x3
	v_add_f32_dpp v202, v202, v202 row_ror:8 row_mask:0xf bank_mask:0x3
	v_add_f32_dpp v203, v203, v203 row_ror:8 row_mask:0xf bank_mask:0x3
	v_add_f32_dpp v204, v204, v204 row_ror:8 row_mask:0xf bank_mask:0x3
	v_add_f32_dpp v205, v205, v205 row_ror:8 row_mask:0xf bank_mask:0x3
	v_add_f32_dpp v206, v206, v206 row_ror:8 row_mask:0xf bank_mask:0xc
	v_add_f32_dpp v207, v207, v207 row_ror:8 row_mask:0xf bank_mask:0xc
	v_add_f32_dpp v208, v208, v208 row_ror:8 row_mask:0xf bank_mask:0xc
	v_add_f32_dpp v209, v209, v209 row_ror:8 row_mask:0xf bank_mask:0xc
	v_add_f32_dpp v210, v210, v210 row_ror:8 row_mask:0xf bank_mask:0xc
	v_add_f32_dpp v211, v211, v211 row_ror:8 row_mask:0xf bank_mask:0xc
	v_add_f32_dpp v212, v212, v212 row_ror:8 row_mask:0xf bank_mask:0xc
	v_add_f32_dpp v213, v213, v213 row_ror:8 row_mask:0xf bank_mask:0xc
	v_mov_b32_dpp v198, v206 quad_perm:[0,1,2,3] row_mask:0xf bank_mask:0xc
	v_mov_b32_dpp v199, v207 quad_perm:[0,1,2,3] row_mask:0xf bank_mask:0xc
	v_mov_b32_dpp v200, v208 quad_perm:[0,1,2,3] row_mask:0xf bank_mask:0xc
	v_mov_b32_dpp v201, v209 quad_perm:[0,1,2,3] row_mask:0xf bank_mask:0xc
	v_mov_b32_dpp v202, v210 quad_perm:[0,1,2,3] row_mask:0xf bank_mask:0xc
	v_mov_b32_dpp v203, v211 quad_perm:[0,1,2,3] row_mask:0xf bank_mask:0xc
	v_mov_b32_dpp v204, v212 quad_perm:[0,1,2,3] row_mask:0xf bank_mask:0xc
	v_mov_b32_dpp v205, v213 quad_perm:[0,1,2,3] row_mask:0xf bank_mask:0xc
	s_waitcnt lgkmcnt(0)
	v_lshl_add_u32 v178, v178, 8, v138
	v_lshl_add_u32 v179, v179, 8, v138
	v_lshl_add_u32 v180, v180, 8, v138
	v_lshl_add_u32 v181, v181, 8, v138
	buffer_load_dwordx4 v[112:115], v178, s[16:19], s26 offen
	buffer_load_dwordx4 v[116:119], v179, s[16:19], s26 offen
	buffer_load_dwordx4 v[120:123], v180, s[16:19], s26 offen
	buffer_load_dwordx4 v[124:127], v181, s[16:19], s26 offen
	s_nop 1
	v_permlane16_swap_b32_e32 v198, v202
	v_add_f32_e32 v198, v198, v202
	v_permlane16_swap_b32_e32 v199, v203
	v_add_f32_e32 v199, v199, v203
	v_permlane16_swap_b32_e32 v200, v204
	v_add_f32_e32 v200, v200, v204
	v_permlane16_swap_b32_e32 v201, v205
	v_add_f32_e32 v201, v201, v205
	s_nop 0
	v_permlane32_swap_b32_e32 v198, v200
	v_add_f32_e32 v198, v198, v200
	v_permlane32_swap_b32_e32 v199, v201
	v_add_f32_e32 v199, v199, v201
	s_ashr_i32 s81, s80, 31
	s_lshl_b64 s[10:11], s[80:81], 12
	s_add_u32 s10, s14, s10
	s_addc_u32 s11, s15, s11
	v_mul_f32_e32 v198, v198, v149
	v_mul_f32_e32 v199, v199, v149
	v_cvt_pk_bf16_f32 v214, v198, v199
	global_store_dword v238, v214, s[10:11] offset:2048
	s_addk_i32 s80, 0x100
	s_cmpk_gt_i32 s80, 0x3fff
	s_cbranch_scc0 .Latt_unit
	s_waitcnt vmcnt(0)
